# FFN weight conversion moved from phase-step 8 (all WGs) to step 9 onto the 128 workgroups without an XQ GEMM tile
# speedup vs baseline: 1.0090x; 1.0044x over previous
; DI void cvt_job(const float* __restrict__ src, int K, int N, int Npad, bf16_t* __restrict__ dst, int mode, float* tile, const int tid) {
;     const int nkt = K / 64, ntile = nkt * (Npad / 256);
;     const int r = tid >> 6, c = (tid & 63) * 4, u0 = c >> 6, cc = c & 63, wn = tid >> 3, kc = (tid & 7) * 8;
;     for (int t = blockIdx.x; t < ntile; t += gridDim.x) {
; DI void run_phase(const Params& P, int ph, unsigned char* shm, const int rep) {
;     ...
;     { int jlo = 0, jhi = 0, lw = l;
;       if (s == -1) { jhi = 10; } else if (s == 8) { jlo = 10; jhi = 13; } else if (s == 15 && more) { jhi = 10; lw = l + 1; }
;       if (jhi > jlo) convert_jobs(P, lw, jlo, jhi, shm); }
.LBB0_449:
	s_and_b64 s[0:1], s[58:59], s[60:61]
	s_and_b64 s[6:7], s[0:1], exec
	s_cselect_b32 s5, 10, 0
	s_mov_b32 s93, s2
	s_mov_b32 s94, s3
	s_mov_b32 s89, s75
	s_mov_b32 s90, s91
	s_and_b64 s[6:7], s[54:55], exec
	s_cselect_b32 s5, 10, s5
	v_writelane_b32 v242, s20, 36
	s_mov_b32 s20, 0
	s_cmp_lg_u32 s83, 9
	s_cbranch_scc1 .Lcvt_sel_done
	s_cmp_lt_u32 s2, 0x80
	s_cbranch_scc1 .Lcvt_sel_done
	s_mov_b32 s5, 13
	s_mov_b32 s20, 10
	s_sub_i32 s93, s2, 0x80
	s_movk_i32 s94, 0x80
	s_lshl_b32 s89, s93, 6
	s_movk_i32 s90, 0x2000
.Lcvt_sel_done:
	s_cmp_le_u32 s5, s20
	v_readlane_b32 s40, v242, 13
	v_readlane_b32 s41, v242, 14
	s_movk_i32 s46, 0xfff
	s_movk_i32 s47, 0xffe0
	s_movk_i32 s49, 0x7e0
	s_mov_b32 s60, 0x4c80000
	s_cbranch_scc1 .LBB0_519
	v_mov_b32_e32 v0, v193
	s_waitcnt vmcnt(7)
	v_mov_b32_e32 v2, s86
	ds_read_b64 v[2:3], v2
	s_or_b64 s[6:7], s[54:55], s[56:57]
	s_and_b64 s[10:11], s[0:1], exec
	s_cselect_b32 s10, s4, s64
	s_and_b64 s[6:7], s[6:7], exec
	s_waitcnt lgkmcnt(0)
	v_readfirstlane_b32 s6, v2
	v_lshlrev_b32_e32 v2, 2, v0
	v_readfirstlane_b32 s7, v3
	s_waitcnt vmcnt(3)
	v_ashrrev_i32_e32 v35, 6, v0
	v_and_b32_e32 v34, 0xfc, v2
	v_ashrrev_i32_e32 v44, 3, v0
	v_lshlrev_b32_e32 v3, 3, v0
	v_lshlrev_b32_e32 v0, 4, v0
	v_bfe_u32 v2, v2, 6, 2
	v_and_b32_e32 v3, 56, v3
	v_and_b32_e32 v0, 0xf0, v0
	v_mul_u32_u24_e32 v2, 0x4100, v2
	v_add3_u32 v2, 0, v0, v2
	v_lshlrev_b32_e32 v0, 1, v3
	v_lshl_add_u64 v[36:37], s[6:7], 0, v[0:1]
	s_movk_i32 s6, 0x104
	s_cselect_b32 s10, s64, s10
	v_lshl_add_u32 v4, v44, 2, 0
	v_mul_u32_u24_e32 v0, 0x104, v3
	v_mul_lo_u32 v3, v35, s6
	s_ashr_i32 s11, s10, 31
	v_and_b32_e32 v45, 0x7f, v44
	s_waitcnt vmcnt(2)
	v_add_u32_e32 v46, v2, v3
	v_add_u32_e32 v47, v4, v0
	s_branch .LBB0_452

;     DI const float* in(int i) const { return (const float*)gp(i); }
;     DI unsigned char* ws() const { return (unsigned char*)gp(35); }
; DI void cvt_job(const float* __restrict__ src, int K, int N, int Npad, bf16_t* __restrict__ dst, int mode, float* tile, const int tid) {
;     const int nkt = K / 64, ntile = nkt * (Npad / 256);
;     const int r = tid >> 6, c = (tid & 63) * 4, u0 = c >> 6, cc = c & 63, wn = tid >> 3, kc = (tid & 7) * 8;
;     for (int t = blockIdx.x; t < ntile; t += gridDim.x) {
;         const int nt_ = t / nkt, kt = t - nt_ * nkt, k0 = kt * 64, n0 = nt_ * 256;
; DI void convert_jobs(const Params& P, int l, int jlo, int jhi, unsigned char* shm) {
;     ...
;         cvt_job(P.in(ii) + (size_t)l * K * N, K, N, Npad, (bf16_t*)(ws + off), mode, tile, tid_);
.LBB0_496:
	s_lshl_b32 s16, s16, 3
	s_add_i32 s16, s16, 0
	s_add_i32 s16, s16, 0x25200
	v_mov_b32_e32 v0, s16
	ds_read_b64 v[2:3], v0
	s_lshr_b32 s16, s14, 6
	s_mul_i32 s17, s17, s16
	s_cmp_ge_i32 s93, s17
	s_waitcnt lgkmcnt(0)
	v_readfirstlane_b32 s22, v3
	v_readfirstlane_b32 s24, v2
	s_cbranch_scc1 .LBB0_451
	v_cvt_f32_u32_e32 v2, s16
	s_mul_i32 s25, s14, s11
	s_mul_hi_u32 s28, s14, s10
	s_add_i32 s25, s28, s25
	v_rcp_iflag_f32_e32 v2, v2
	s_mul_i32 s28, s14, s10
	s_mul_i32 s25, s25, s12
	s_mul_hi_u32 s29, s28, s12
	v_mul_f32_e32 v2, 0x4f7ffffe, v2
	s_add_i32 s29, s29, s25
	s_mul_i32 s28, s28, s12
	v_cvt_u32_f32_e32 v2, v2
	s_lshl_b64 s[28:29], s[28:29], 2
	s_add_u32 s24, s24, s28
	s_addc_u32 s25, s22, s29
	v_lshlrev_b32_e32 v0, 2, v34
	v_lshl_add_u64 v[38:39], s[24:25], 0, v[0:1]
	s_sub_i32 s22, 0, s16
	v_readfirstlane_b32 s24, v2
	s_mul_i32 s22, s22, s24
	s_mul_hi_u32 s22, s24, s22
	s_add_i32 s22, s24, s22
	s_lshl_b32 s24, s16, 6
	v_lshl_add_u64 v[40:41], v[36:37], 0, s[54:55]
	v_or_b32_e32 v0, s15, v45
	s_sub_i32 s24, 0, s24
	s_mov_b32 s25, s89
	s_mov_b32 s28, s93
	s_branch .LBB0_499

; DI unsigned cvtpk(float lo, float hi) { unsigned r; asm volatile("v_cvt_pk_bf16_f32 %0, %1, %2" : "=v"(r) : "v"(lo), "v"(hi)); return r; }
; DI void cvt_job(const float* __restrict__ src, int K, int N, int Npad, bf16_t* __restrict__ dst, int mode, float* tile, const int tid) {
;     ...
;         __syncthreads();
; #pragma unroll
;         for (int i = 0; i < 8; ++i) { float* tp = tile + u0 * 4160 + (r + 8 * i) * 65 + cc; tp[0] = v[i][0]; tp[1] = v[i][1]; tp[2] = v[i][2]; tp[3] = v[i][3]; }
;         __syncthreads();
; #pragma unroll
;         for (int u = 0; u < 4; ++u) {
;             float x[8];
; #pragma unroll
;             for (int j = 0; j < 8; ++j) x[j] = tile[u * 4160 + (kc + j) * 65 + wn];
;             const int n = n0 + u * 64 + wn; const int drow = mode == 0 ? n : ((n >> 7) * 256 + (mode == 2 ? 128 : 0) + (n & 127));
;             u32x4 w; w.x = cvtpk(x[0], x[1]); w.y = cvtpk(x[2], x[3]); w.z = cvtpk(x[4], x[5]); w.w = cvtpk(x[6], x[7]);
;             *(u32x4*)(dst + (size_t)drow * K + k0 + kc) = w;
;         }
;     }
.Lcvt_noscale:
	ds_write2_b32 v46, v6, v7 offset1:1
	ds_write2_b32 v46, v8, v9 offset0:2 offset1:3
	v_add_u32_e32 v6, 0x820, v46
	ds_write2_b32 v6, v2, v3 offset1:1
	v_add_u32_e32 v2, 0x828, v46
	ds_write2_b32 v2, v4, v5 offset1:1
	v_add_u32_e32 v2, 0x1040, v46
	ds_write2_b32 v2, v14, v15 offset1:1
	v_add_u32_e32 v2, 0x1048, v46
	ds_write2_b32 v2, v16, v17 offset1:1
	v_add_u32_e32 v2, 0x1860, v46
	ds_write2_b32 v2, v10, v11 offset1:1
	v_add_u32_e32 v2, 0x1868, v46
	ds_write2_b32 v2, v12, v13 offset1:1
	v_add_u32_e32 v2, 0x2080, v46
	ds_write2_b32 v2, v22, v23 offset1:1
	v_add_u32_e32 v2, 0x2088, v46
	ds_write2_b32 v2, v24, v25 offset1:1
	v_add_u32_e32 v2, 0x28a0, v46
	ds_write2_b32 v2, v18, v19 offset1:1
	v_add_u32_e32 v2, 0x28a8, v46
	ds_write2_b32 v2, v20, v21 offset1:1
	v_add_u32_e32 v2, 0x30c0, v46
	ds_write2_b32 v2, v30, v31 offset1:1
	v_add_u32_e32 v2, 0x30c8, v46
	ds_write2_b32 v2, v32, v33 offset1:1
	v_add_u32_e32 v2, 0x38e0, v46
	ds_write2_b32 v2, v26, v27 offset1:1
	v_add_u32_e32 v2, 0x38e8, v46
	v_add_u32_e32 v12, s56, v44
	ds_write2_b32 v2, v28, v29 offset1:1
	v_lshlrev_b32_e32 v2, 1, v12
	s_waitcnt lgkmcnt(0)
	s_barrier
	v_and_or_b32 v13, v2, s30, v0
	ds_read2_b32 v[2:3], v47 offset1:65
	ds_read2_b32 v[4:5], v47 offset0:130 offset1:195
	v_add_u32_e32 v10, 0x400, v47
	ds_read2_b32 v[8:9], v10 offset0:4 offset1:69
	ds_read2_b32 v[10:11], v10 offset0:134 offset1:199
	v_cndmask_b32_e64 v13, v13, v12, s[6:7]
	s_waitcnt lgkmcnt(3)
	v_cvt_pk_bf16_f32 v2, v2, v3
	s_waitcnt lgkmcnt(2)
	v_cvt_pk_bf16_f32 v3, v4, v5
	s_waitcnt lgkmcnt(1)
	v_cvt_pk_bf16_f32 v4, v8, v9
	v_mad_u64_u32 v[8:9], s[36:37], v13, s14, 0
	s_waitcnt lgkmcnt(0)
	v_cvt_pk_bf16_f32 v5, v10, v11
	v_ashrrev_i32_e32 v11, 31, v13
	v_mov_b32_e32 v10, v9
	s_ashr_i32 s55, s54, 31
	v_mad_u64_u32 v[10:11], s[36:37], v11, s14, v[10:11]
	v_lshl_add_u64 v[6:7], s[54:55], 1, v[40:41]
	v_mov_b32_e32 v9, v10
	v_lshl_add_u64 v[8:9], v[8:9], 1, v[6:7]
	v_add_u32_e32 v13, 64, v12
	global_store_dwordx4 v[8:9], v[2:5], off
	v_add_u32_e32 v8, 0x4400, v47
	ds_read2_b32 v[8:9], v8 offset0:68 offset1:133
	v_lshlrev_b32_e32 v2, 1, v13
	v_and_b32_e32 v2, 0xffffff00, v2
	v_and_b32_e32 v3, 0x7f, v13
	v_or3_b32 v14, v3, v2, s15
	v_add_u32_e32 v2, 0x4000, v47
	v_add_u32_e32 v4, 0x4200, v47
	ds_read2_b32 v[2:3], v2 offset0:64 offset1:129
	ds_read2_b32 v[4:5], v4 offset0:66 offset1:131
	v_add_u32_e32 v10, 0x4600, v47
	v_cndmask_b32_e64 v13, v14, v13, s[6:7]
	ds_read2_b32 v[10:11], v10 offset0:70 offset1:135
	s_waitcnt lgkmcnt(2)
	v_cvt_pk_bf16_f32 v2, v2, v3
	s_waitcnt lgkmcnt(1)
	v_cvt_pk_bf16_f32 v3, v4, v5
	v_cvt_pk_bf16_f32 v4, v8, v9
	v_mad_u64_u32 v[8:9], s[36:37], v13, s14, 0
	s_waitcnt lgkmcnt(0)
	v_cvt_pk_bf16_f32 v5, v10, v11
	v_ashrrev_i32_e32 v11, 31, v13
	v_mov_b32_e32 v10, v9
	v_mad_u64_u32 v[10:11], s[36:37], v11, s14, v[10:11]
	v_mov_b32_e32 v9, v10
	v_lshl_add_u64 v[8:9], v[8:9], 1, v[6:7]
	v_add_u32_e32 v13, 0x80, v12
	global_store_dwordx4 v[8:9], v[2:5], off
	v_add_u32_e32 v8, 0x8400, v47
	v_add_u32_e32 v10, 0x8800, v47
	v_lshlrev_b32_e32 v2, 1, v13
	v_and_or_b32 v14, v2, s30, v0
	v_add_u32_e32 v2, 0x8000, v47
	ds_read2_b32 v[2:3], v2 offset0:128 offset1:193
	ds_read2_b32 v[4:5], v8 offset0:2 offset1:67
	ds_read2_b32 v[8:9], v8 offset0:132 offset1:197
	v_cndmask_b32_e64 v13, v14, v13, s[6:7]
	ds_read2_b32 v[10:11], v10 offset0:6 offset1:71
	s_waitcnt lgkmcnt(3)
	v_cvt_pk_bf16_f32 v2, v2, v3
	s_waitcnt lgkmcnt(2)
	v_cvt_pk_bf16_f32 v3, v4, v5
	s_waitcnt lgkmcnt(1)
	v_cvt_pk_bf16_f32 v4, v8, v9
	v_mad_u64_u32 v[8:9], s[36:37], v13, s14, 0
	s_waitcnt lgkmcnt(0)
	v_cvt_pk_bf16_f32 v5, v10, v11
	v_ashrrev_i32_e32 v11, 31, v13
	v_mov_b32_e32 v10, v9
	v_mad_u64_u32 v[10:11], s[36:37], v11, s14, v[10:11]
	v_mov_b32_e32 v9, v10
	v_lshl_add_u64 v[8:9], v[8:9], 1, v[6:7]
	v_add_u32_e32 v12, 0xc0, v12
	global_store_dwordx4 v[8:9], v[2:5], off
	v_add_u32_e32 v8, 0xc600, v47
	ds_read2_b32 v[8:9], v8 offset0:68 offset1:133
	v_lshlrev_b32_e32 v2, 1, v12
	v_and_b32_e32 v2, 0xffffff00, v2
	v_and_b32_e32 v3, 0x7f, v12
	v_or3_b32 v13, v3, v2, s15
	v_add_u32_e32 v2, 0xc200, v47
	v_add_u32_e32 v4, 0xc400, v47
	ds_read2_b32 v[2:3], v2 offset0:64 offset1:129
	ds_read2_b32 v[4:5], v4 offset0:66 offset1:131
	v_add_u32_e32 v10, 0xc800, v47
	v_cndmask_b32_e64 v12, v13, v12, s[6:7]
	ds_read2_b32 v[10:11], v10 offset0:70 offset1:135
	s_waitcnt lgkmcnt(2)
	v_cvt_pk_bf16_f32 v2, v2, v3
	s_waitcnt lgkmcnt(1)
	v_cvt_pk_bf16_f32 v3, v4, v5
	v_cvt_pk_bf16_f32 v4, v8, v9
	v_mad_u64_u32 v[8:9], s[36:37], v12, s14, 0
	s_waitcnt lgkmcnt(0)
	v_cvt_pk_bf16_f32 v5, v10, v11
	v_ashrrev_i32_e32 v11, 31, v12
	v_mov_b32_e32 v10, v9
	v_mad_u64_u32 v[10:11], s[36:37], v11, s14, v[10:11]
	v_mov_b32_e32 v9, v10
	s_add_i32 s28, s28, s94
	s_add_i32 s25, s25, s90
	v_lshl_add_u64 v[6:7], v[8:9], 1, v[6:7]
	s_cmp_lt_i32 s28, s17
	global_store_dwordx4 v[6:7], v[2:5], off
	s_cbranch_scc0 .LBB0_451
